# grid barrier: first poll no longer waits for the hoisted L1 invalidate (completion still awaited before the closing s_barrier)
# speedup vs baseline: 1.0030x; 1.0030x over previous
.LBB0_86:
	v_readlane_b32 s4, v243, 5
	s_lshl_b32 s4, s4, 8
	v_readlane_b32 s6, v243, 3
	v_readlane_b32 s7, v243, 4
	s_add_u32 s4, s6, s4
	s_addc_u32 s5, s7, 0
	v_mov_b32_e32 v1, 0x1000
	v_mov_b32_e32 v3, 1
	global_atomic_add v3, v1, v3, s[4:5] offset:1024 sc0
	v_cvt_f32_u32_e32 v1, v2
	v_sub_u32_e32 v4, 0, v2
	v_rcp_iflag_f32_e32 v1, v1
	s_nop 0
	v_mul_f32_e32 v1, 0x4f7ffffe, v1
	v_cvt_u32_f32_e32 v1, v1
	v_mul_lo_u32 v4, v4, v1
	v_mul_hi_u32 v4, v1, v4
	v_add_u32_e32 v1, v1, v4
	s_waitcnt vmcnt(0)
	v_mul_hi_u32 v1, v3, v1
	v_mul_lo_u32 v4, v1, v2
	v_sub_u32_e32 v4, v3, v4
	v_add_u32_e32 v5, 1, v1
	v_cmp_ge_u32_e32 vcc, v4, v2
	v_add_u32_e32 v3, 1, v3
	s_nop 0
	v_cndmask_b32_e32 v1, v1, v5, vcc
	v_sub_u32_e32 v5, v4, v2
	v_cndmask_b32_e32 v4, v4, v5, vcc
	v_add_u32_e32 v5, 1, v1
	v_cmp_ge_u32_e32 vcc, v4, v2
	s_nop 1
	v_cndmask_b32_e32 v1, v1, v5, vcc
	v_mul_lo_u32 v4, v2, v1
	v_add_u32_e32 v2, v4, v2
	v_cmp_ne_u32_e32 vcc, v3, v2
	s_and_saveexec_b64 s[6:7], vcc
	s_xor_b64 s[6:7], exec, s[6:7]
	s_cbranch_execz .LBB0_100
	s_waitcnt lgkmcnt(0)
	v_mad_u32_u24 v16, v1, v0, v0
	buffer_inv sc1
	v_mov_b32_e32 v0, 0xc3000
	global_load_dword v0, v0, s[92:93] offset:1024 sc1
	s_add_u32 s12, s92, 0xc3400
	s_addc_u32 s13, s93, 0
	s_waitcnt vmcnt(0)
	v_cmp_lt_u32_e32 vcc, v0, v16
	s_and_saveexec_b64 s[8:9], vcc
	s_cbranch_execz .LBB0_99
	s_add_u32 s10, s92, 0xc0200
	s_addc_u32 s11, s93, 0
	s_mov_b32 s26, 1
	s_mov_b64 s[16:17], 0
	v_mov_b32_e32 v0, 0
	s_branch .LBB0_90

.LBB0_391:
	v_readlane_b32 s4, v243, 5
	s_lshl_b32 s4, s4, 8
	v_readlane_b32 s6, v243, 3
	v_readlane_b32 s7, v243, 4
	s_add_u32 s4, s6, s4
	s_addc_u32 s5, s7, 0
	v_mov_b32_e32 v1, 0x1000
	v_mov_b32_e32 v3, 1
	global_atomic_add v3, v1, v3, s[4:5] offset:1024 sc0
	v_cvt_f32_u32_e32 v1, v2
	v_sub_u32_e32 v4, 0, v2
	v_rcp_iflag_f32_e32 v1, v1
	s_nop 0
	v_mul_f32_e32 v1, 0x4f7ffffe, v1
	v_cvt_u32_f32_e32 v1, v1
	v_mul_lo_u32 v4, v4, v1
	v_mul_hi_u32 v4, v1, v4
	v_add_u32_e32 v1, v1, v4
	s_waitcnt vmcnt(0)
	v_mul_hi_u32 v1, v3, v1
	v_mul_lo_u32 v4, v1, v2
	v_sub_u32_e32 v4, v3, v4
	v_add_u32_e32 v5, 1, v1
	v_cmp_ge_u32_e32 vcc, v4, v2
	v_add_u32_e32 v3, 1, v3
	s_nop 0
	v_cndmask_b32_e32 v1, v1, v5, vcc
	v_sub_u32_e32 v5, v4, v2
	v_cndmask_b32_e32 v4, v4, v5, vcc
	v_add_u32_e32 v5, 1, v1
	v_cmp_ge_u32_e32 vcc, v4, v2
	s_nop 1
	v_cndmask_b32_e32 v1, v1, v5, vcc
	v_mul_lo_u32 v4, v2, v1
	v_add_u32_e32 v2, v4, v2
	v_cmp_ne_u32_e32 vcc, v3, v2
	s_and_saveexec_b64 s[6:7], vcc
	s_xor_b64 s[6:7], exec, s[6:7]
	s_cbranch_execz .LBB0_405
	s_waitcnt lgkmcnt(0)
	v_mad_u32_u24 v16, v1, v0, v0
	buffer_inv sc1
	v_mov_b32_e32 v0, 0xc3000
	global_load_dword v0, v0, s[92:93] offset:1024 sc1
	s_add_u32 s14, s92, 0xc3400
	s_addc_u32 s15, s93, 0
	s_waitcnt vmcnt(0)
	v_cmp_lt_u32_e32 vcc, v0, v16
	s_and_saveexec_b64 s[8:9], vcc
	s_cbranch_execz .LBB0_404
	s_add_u32 s10, s92, 0xc0200
	s_addc_u32 s11, s93, 0
	s_mov_b32 s26, 1
	s_mov_b64 s[16:17], 0
	v_mov_b32_e32 v0, 0
	s_branch .LBB0_395

.LBB0_606:
	v_readlane_b32 s2, v243, 5
	s_lshl_b32 s2, s2, 8
	v_readlane_b32 s4, v243, 3
	v_readlane_b32 s5, v243, 4
	s_add_u32 s2, s4, s2
	s_addc_u32 s3, s5, 0
	v_mov_b32_e32 v1, 0x1000
	v_mov_b32_e32 v3, 1
	global_atomic_add v3, v1, v3, s[2:3] offset:1024 sc0
	v_cvt_f32_u32_e32 v1, v2
	v_sub_u32_e32 v4, 0, v2
	v_rcp_iflag_f32_e32 v1, v1
	s_nop 0
	v_mul_f32_e32 v1, 0x4f7ffffe, v1
	v_cvt_u32_f32_e32 v1, v1
	v_mul_lo_u32 v4, v4, v1
	v_mul_hi_u32 v4, v1, v4
	v_add_u32_e32 v1, v1, v4
	s_waitcnt vmcnt(0)
	v_mul_hi_u32 v1, v3, v1
	v_mul_lo_u32 v4, v1, v2
	v_sub_u32_e32 v4, v3, v4
	v_add_u32_e32 v5, 1, v1
	v_cmp_ge_u32_e32 vcc, v4, v2
	v_add_u32_e32 v3, 1, v3
	s_nop 0
	v_cndmask_b32_e32 v1, v1, v5, vcc
	v_sub_u32_e32 v5, v4, v2
	v_cndmask_b32_e32 v4, v4, v5, vcc
	v_add_u32_e32 v5, 1, v1
	v_cmp_ge_u32_e32 vcc, v4, v2
	s_nop 1
	v_cndmask_b32_e32 v1, v1, v5, vcc
	v_mul_lo_u32 v4, v2, v1
	v_add_u32_e32 v2, v4, v2
	v_cmp_ne_u32_e32 vcc, v3, v2
	s_and_saveexec_b64 s[4:5], vcc
	s_xor_b64 s[4:5], exec, s[4:5]
	s_cbranch_execz .LBB0_620
	s_waitcnt lgkmcnt(0)
	v_mad_u32_u24 v16, v1, v0, v0
	buffer_inv sc1
	v_mov_b32_e32 v0, 0xc3000
	global_load_dword v0, v0, s[92:93] offset:1024 sc1
	s_add_u32 s10, s92, 0xc3400
	s_addc_u32 s11, s93, 0
	s_waitcnt vmcnt(0)
	v_cmp_lt_u32_e32 vcc, v0, v16
	s_and_saveexec_b64 s[6:7], vcc
	s_cbranch_execz .LBB0_619
	s_add_u32 s8, s92, 0xc0200
	s_addc_u32 s9, s93, 0
	s_mov_b32 s24, 1
	s_mov_b64 s[14:15], 0
	v_mov_b32_e32 v0, 0
	s_branch .LBB0_610

.LBB0_1114:
	v_readlane_b32 s4, v243, 5
	s_lshl_b32 s4, s4, 8
	v_readlane_b32 s6, v243, 3
	v_readlane_b32 s7, v243, 4
	s_add_u32 s4, s6, s4
	s_addc_u32 s5, s7, 0
	v_mov_b32_e32 v1, 0x1000
	v_mov_b32_e32 v3, 1
	global_atomic_add v3, v1, v3, s[4:5] offset:1024 sc0
	v_cvt_f32_u32_e32 v1, v2
	v_sub_u32_e32 v4, 0, v2
	v_rcp_iflag_f32_e32 v1, v1
	s_nop 0
	v_mul_f32_e32 v1, 0x4f7ffffe, v1
	v_cvt_u32_f32_e32 v1, v1
	v_mul_lo_u32 v4, v4, v1
	v_mul_hi_u32 v4, v1, v4
	v_add_u32_e32 v1, v1, v4
	s_waitcnt vmcnt(0)
	v_mul_hi_u32 v1, v3, v1
	v_mul_lo_u32 v4, v1, v2
	v_sub_u32_e32 v4, v3, v4
	v_add_u32_e32 v5, 1, v1
	v_cmp_ge_u32_e32 vcc, v4, v2
	v_add_u32_e32 v3, 1, v3
	s_nop 0
	v_cndmask_b32_e32 v1, v1, v5, vcc
	v_sub_u32_e32 v5, v4, v2
	v_cndmask_b32_e32 v4, v4, v5, vcc
	v_add_u32_e32 v5, 1, v1
	v_cmp_ge_u32_e32 vcc, v4, v2
	s_nop 1
	v_cndmask_b32_e32 v1, v1, v5, vcc
	v_mul_lo_u32 v4, v2, v1
	v_add_u32_e32 v2, v4, v2
	v_cmp_ne_u32_e32 vcc, v3, v2
	s_and_saveexec_b64 s[6:7], vcc
	s_xor_b64 s[6:7], exec, s[6:7]
	s_cbranch_execz .LBB0_1128
	s_waitcnt lgkmcnt(0)
	v_mad_u32_u24 v16, v1, v0, v0
	buffer_inv sc1
	v_mov_b32_e32 v0, 0xc3000
	global_load_dword v0, v0, s[92:93] offset:1024 sc1
	s_add_u32 s18, s92, 0xc3400
	s_addc_u32 s19, s93, 0
	s_waitcnt vmcnt(0)
	v_cmp_lt_u32_e32 vcc, v0, v16
	s_and_saveexec_b64 s[8:9], vcc
	s_cbranch_execz .LBB0_1127
	s_add_u32 s12, s92, 0xc0200
	s_addc_u32 s13, s93, 0
	s_mov_b32 s14, 1
	s_mov_b64 s[20:21], 0
	v_mov_b32_e32 v0, 0
	s_branch .LBB0_1118

.LBB0_1350:
	v_readlane_b32 s4, v243, 5
	s_lshl_b32 s4, s4, 8
	v_readlane_b32 s6, v243, 3
	v_readlane_b32 s7, v243, 4
	s_add_u32 s4, s6, s4
	s_addc_u32 s5, s7, 0
	v_mov_b32_e32 v1, 0x1000
	v_mov_b32_e32 v3, 1
	global_atomic_add v3, v1, v3, s[4:5] offset:1024 sc0
	v_cvt_f32_u32_e32 v1, v2
	v_sub_u32_e32 v4, 0, v2
	v_rcp_iflag_f32_e32 v1, v1
	s_nop 0
	v_mul_f32_e32 v1, 0x4f7ffffe, v1
	v_cvt_u32_f32_e32 v1, v1
	v_mul_lo_u32 v4, v4, v1
	v_mul_hi_u32 v4, v1, v4
	v_add_u32_e32 v1, v1, v4
	s_waitcnt vmcnt(0)
	v_mul_hi_u32 v1, v3, v1
	v_mul_lo_u32 v4, v1, v2
	v_sub_u32_e32 v4, v3, v4
	v_add_u32_e32 v5, 1, v1
	v_cmp_ge_u32_e32 vcc, v4, v2
	v_add_u32_e32 v3, 1, v3
	s_nop 0
	v_cndmask_b32_e32 v1, v1, v5, vcc
	v_sub_u32_e32 v5, v4, v2
	v_cndmask_b32_e32 v4, v4, v5, vcc
	v_add_u32_e32 v5, 1, v1
	v_cmp_ge_u32_e32 vcc, v4, v2
	s_nop 1
	v_cndmask_b32_e32 v1, v1, v5, vcc
	v_mul_lo_u32 v4, v2, v1
	v_add_u32_e32 v2, v4, v2
	v_cmp_ne_u32_e32 vcc, v3, v2
	s_and_saveexec_b64 s[6:7], vcc
	s_xor_b64 s[6:7], exec, s[6:7]
	s_cbranch_execz .LBB0_1364
	s_waitcnt lgkmcnt(0)
	v_mad_u32_u24 v16, v1, v0, v0
	buffer_inv sc1
	v_mov_b32_e32 v0, 0xc3000
	global_load_dword v0, v0, s[92:93] offset:1024 sc1
	s_add_u32 s12, s92, 0xc3400
	s_addc_u32 s13, s93, 0
	s_waitcnt vmcnt(0)
	v_cmp_lt_u32_e32 vcc, v0, v16
	s_and_saveexec_b64 s[8:9], vcc
	s_cbranch_execz .LBB0_1363
	s_add_u32 s10, s92, 0xc0200
	s_addc_u32 s11, s93, 0
	s_mov_b32 s24, 1
	s_mov_b64 s[14:15], 0
	v_mov_b32_e32 v0, 0
	s_branch .LBB0_1354

.LBB0_2069:
	v_readlane_b32 s2, v243, 5
	s_lshl_b32 s2, s2, 8
	v_readlane_b32 s4, v243, 3
	v_readlane_b32 s5, v243, 4
	s_add_u32 s2, s4, s2
	s_addc_u32 s3, s5, 0
	v_mov_b32_e32 v1, 0x1000
	v_mov_b32_e32 v3, 1
	global_atomic_add v3, v1, v3, s[2:3] offset:1024 sc0
	v_cvt_f32_u32_e32 v1, v2
	v_sub_u32_e32 v4, 0, v2
	v_rcp_iflag_f32_e32 v1, v1
	s_nop 0
	v_mul_f32_e32 v1, 0x4f7ffffe, v1
	v_cvt_u32_f32_e32 v1, v1
	v_mul_lo_u32 v4, v4, v1
	v_mul_hi_u32 v4, v1, v4
	v_add_u32_e32 v1, v1, v4
	s_waitcnt vmcnt(0)
	v_mul_hi_u32 v1, v3, v1
	v_mul_lo_u32 v4, v1, v2
	v_sub_u32_e32 v4, v3, v4
	v_add_u32_e32 v5, 1, v1
	v_cmp_ge_u32_e32 vcc, v4, v2
	v_add_u32_e32 v3, 1, v3
	s_nop 0
	v_cndmask_b32_e32 v1, v1, v5, vcc
	v_sub_u32_e32 v5, v4, v2
	v_cndmask_b32_e32 v4, v4, v5, vcc
	v_add_u32_e32 v5, 1, v1
	v_cmp_ge_u32_e32 vcc, v4, v2
	s_nop 1
	v_cndmask_b32_e32 v1, v1, v5, vcc
	v_mul_lo_u32 v4, v2, v1
	v_add_u32_e32 v2, v4, v2
	v_cmp_ne_u32_e32 vcc, v3, v2
	s_and_saveexec_b64 s[4:5], vcc
	s_xor_b64 s[4:5], exec, s[4:5]
	s_cbranch_execz .LBB0_2083
	s_waitcnt lgkmcnt(0)
	v_mad_u32_u24 v16, v1, v0, v0
	buffer_inv sc1
	v_mov_b32_e32 v0, 0xc3000
	global_load_dword v0, v0, s[92:93] offset:1024 sc1
	s_add_u32 s10, s92, 0xc3400
	s_addc_u32 s11, s93, 0
	s_waitcnt vmcnt(0)
	v_cmp_lt_u32_e32 vcc, v0, v16
	s_and_saveexec_b64 s[6:7], vcc
	s_cbranch_execz .LBB0_2082
	s_add_u32 s8, s92, 0xc0200
	s_addc_u32 s9, s93, 0
	s_mov_b32 s22, 1
	s_mov_b64 s[12:13], 0
	v_mov_b32_e32 v0, 0
	s_branch .LBB0_2073
